# attention: first K-fragment LDS reads of each half issued right after the barrier (before the softmax bookkeeping)
# speedup vs baseline: 1.0046x; 1.0046x over previous
.LBB0_804:
	s_or_b64 exec, exec, s[8:9]
	global_load_dwordx4 v[146:149], v160, s[56:57] offset:128
	ds_read_b128 v[98:101], v201 offset:13312
	ds_read_b128 v[102:105], v201 offset:13344
	v_max_f32_e32 v83, v50, v51
	v_max3_f32 v84, v52, v53, v67
	v_max3_f32 v83, v83, v66, v68
	v_max3_f32 v83, v83, v69, v54
	v_max3_f32 v84, v84, v56, v57
	v_max3_f32 v83, v83, v55, v70
	v_max3_f32 v84, v84, v72, v73
	v_max3_f32 v83, v83, v71, v58
	v_max3_f32 v84, v84, v60, v61
	v_max3_f32 v83, v83, v59, v74
	v_max3_f32 v84, v84, v76, v77
	v_max3_f32 v83, v83, v75, v62
	v_max3_f32 v84, v84, v64, v65
	v_max3_f32 v83, v83, v63, v78
	v_max3_f32 v84, v84, v80, v81
	v_max3_f32 v83, v83, v79, v84
	v_mov_b32_e32 v84, v83
	s_cmp_eq_u32 s12, 0
	s_nop 0
	v_permlane32_swap_b32_e32 v83, v84
	v_max_f32_e32 v83, v83, v84
	s_cbranch_scc1 .Lat1_first
	v_cmp_lt_f32_e32 vcc, s97, v83
	s_cbranch_vccnz .Lat1_resc
	v_mov_b32_e32 v204, v205
.LBB0_813:
	v_exp_f32_e32 v50, v50
	v_exp_f32_e32 v51, v51
	s_waitcnt lgkmcnt(0)
	v_mfma_f32_32x32x16_bf16 v[82:97], v[98:101], v[114:117], v[34:49]
	v_exp_f32_e32 v52, v52
	v_exp_f32_e32 v53, v53
	v_exp_f32_e32 v54, v54
	v_exp_f32_e32 v55, v55
	v_exp_f32_e32 v56, v56
	v_exp_f32_e32 v57, v57
	v_mfma_f32_32x32x16_bf16 v[82:97], v[102:105], v[118:121], v[82:97]
	ds_read_b128 v[98:101], v201 offset:13376
	ds_read_b128 v[102:105], v201 offset:13408
	v_exp_f32_e32 v58, v58
	v_exp_f32_e32 v59, v59
	v_exp_f32_e32 v60, v60
	v_exp_f32_e32 v61, v61
	v_exp_f32_e32 v62, v62
	v_exp_f32_e32 v63, v63
	s_waitcnt lgkmcnt(0)
	v_mfma_f32_32x32x16_bf16 v[82:97], v[98:101], v[122:125], v[82:97]
	v_exp_f32_e32 v64, v64
	v_exp_f32_e32 v65, v65
	v_exp_f32_e32 v66, v66
	v_exp_f32_e32 v67, v67
	v_exp_f32_e32 v68, v68
	v_exp_f32_e32 v69, v69
	v_exp_f32_e32 v70, v70
	v_mfma_f32_32x32x16_bf16 v[82:97], v[102:105], v[126:129], v[82:97]
	ds_read_b128 v[98:101], v201 offset:13440
	ds_read_b128 v[102:105], v201 offset:13472
	ds_read_b128 v[170:173], v201 offset:19968
	ds_read_b128 v[174:177], v201 offset:20000
	v_exp_f32_e32 v71, v71
	v_exp_f32_e32 v72, v72
	v_exp_f32_e32 v73, v73
	v_exp_f32_e32 v74, v74
	v_exp_f32_e32 v75, v75
	s_waitcnt lgkmcnt(2)
	v_mfma_f32_32x32x16_bf16 v[82:97], v[98:101], v[130:133], v[82:97]
	v_exp_f32_e32 v76, v76
	v_exp_f32_e32 v77, v77
	v_exp_f32_e32 v78, v78
	v_exp_f32_e32 v79, v79
	v_exp_f32_e32 v80, v80
	v_exp_f32_e32 v81, v81
	v_mfma_f32_32x32x16_bf16 v[82:97], v[102:105], v[134:137], v[82:97]
	s_waitcnt lgkmcnt(0)
	v_mfma_f32_32x32x16_bf16 v[98:113], v[170:173], v[114:117], v[34:49]
	v_mfma_f32_32x32x16_bf16 v[98:113], v[174:177], v[118:121], v[98:113]
	ds_read_b128 v[170:173], v201 offset:20032
	ds_read_b128 v[174:177], v201 offset:20064
	s_waitcnt lgkmcnt(0)
	v_mfma_f32_32x32x16_bf16 v[98:113], v[170:173], v[122:125], v[98:113]
	v_mfma_f32_32x32x16_bf16 v[98:113], v[174:177], v[126:129], v[98:113]
	ds_read_b128 v[170:173], v201 offset:20096
	ds_read_b128 v[174:177], v201 offset:20128
	ds_read2_b64 v[180:183], v206 offset0:4 offset1:6
	s_waitcnt lgkmcnt(2)
	v_mfma_f32_32x32x16_bf16 v[98:113], v[170:173], v[130:133], v[98:113]
	ds_read2_b64 v[170:173], v206 offset1:2
	s_waitcnt lgkmcnt(2)
	v_mfma_f32_32x32x16_bf16 v[98:113], v[174:177], v[134:137], v[98:113]
	v_cvt_pk_bf16_f32 v174, v50, v51
	v_cvt_pk_bf16_f32 v175, v52, v53
	v_cvt_pk_bf16_f32 v176, v54, v55
	v_cvt_pk_bf16_f32 v177, v56, v57
	s_waitcnt lgkmcnt(0)
	s_nop 0
	v_mfma_f32_32x32x16_bf16 v[2:17], v[170:173], v[174:177], v[2:17]
	ds_read2_b64 v[170:173], v207 offset0:32 offset1:34
	s_waitcnt lgkmcnt(0)
	v_mfma_f32_32x32x16_bf16 v[18:33], v[170:173], v[174:177], v[18:33]
	ds_read2_b64 v[174:177], v207 offset0:36 offset1:38
	v_cvt_pk_bf16_f32 v170, v58, v59
	v_cvt_pk_bf16_f32 v171, v60, v61
	v_cvt_pk_bf16_f32 v172, v62, v63
	v_cvt_pk_bf16_f32 v173, v64, v65
	s_nop 1
	v_mfma_f32_32x32x16_bf16 v[2:17], v[180:183], v[170:173], v[2:17]
	ds_read2_b64 v[180:183], v206 offset0:8 offset1:10
	s_waitcnt lgkmcnt(1)
	v_mfma_f32_32x32x16_bf16 v[18:33], v[174:177], v[170:173], v[18:33]
	ds_read2_b64 v[174:177], v207 offset0:40 offset1:42
	v_cvt_pk_bf16_f32 v170, v66, v67
	v_cvt_pk_bf16_f32 v171, v68, v69
	v_cvt_pk_bf16_f32 v172, v70, v71
	v_cvt_pk_bf16_f32 v173, v72, v73
	s_waitcnt lgkmcnt(1)
	s_nop 0
	v_mfma_f32_32x32x16_bf16 v[2:17], v[180:183], v[170:173], v[2:17]
	ds_read2_b64 v[180:183], v206 offset0:12 offset1:14
	s_waitcnt lgkmcnt(1)
	v_mfma_f32_32x32x16_bf16 v[18:33], v[174:177], v[170:173], v[18:33]
	ds_read2_b64 v[174:177], v207 offset0:44 offset1:46
	v_cvt_pk_bf16_f32 v170, v74, v75
	v_cvt_pk_bf16_f32 v171, v76, v77
	v_cvt_pk_bf16_f32 v172, v78, v79
	v_cvt_pk_bf16_f32 v173, v80, v81
	s_waitcnt vmcnt(1)
	ds_write_b128 v190, v[142:145]
	s_waitcnt lgkmcnt(2)
	v_mfma_f32_32x32x16_bf16 v[2:17], v[180:183], v[170:173], v[2:17]
	s_waitcnt lgkmcnt(1)
	v_mfma_f32_32x32x16_bf16 v[18:33], v[174:177], v[170:173], v[18:33]
	s_and_saveexec_b64 s[8:9], s[6:7]
	ds_write_b128 v241, v[138:141]
	s_or_b64 exec, exec, s[8:9]
	s_waitcnt vmcnt(0)
	ds_write2_b64 v208, v[146:147], v[148:149] offset1:1
	s_waitcnt lgkmcnt(0)
	s_barrier
	global_load_dwordx4 v[142:145], v152, s[54:55]
	s_and_saveexec_b64 s[8:9], s[6:7]
	s_cbranch_execz .LBB0_817
	global_load_dwordx4 v[138:141], v150, s[54:55]
; DI float rowmax32(const f32x16& p0, const f32x16& p1) {
;     float a = fmaxf(fmaxf(p0[0], p0[1]), p1[0]), b = fmaxf(fmaxf(p0[2], p0[3]), p1[1]); a = fmaxf(fmaxf(a, p1[2]), p1[3]);
; #pragma unroll
;     for (int r = 4; r < 16; r += 4) { a = fmaxf(fmaxf(a, p0[r]), p0[r + 1]); b = fmaxf(fmaxf(b, p0[r + 2]), p0[r + 3]); a = fmaxf(fmaxf(a, p1[r]), p1[r + 1]); b = fmaxf(fmaxf(b, p1[r + 2]), p1[r + 3]); }
;     const float m = fmaxf(a, b);
;     const auto rr = __builtin_amdgcn_permlane32_swap(__float_as_uint(m), __float_as_uint(m), false, false);
;     return fmaxf(__uint_as_float(rr[0]), __uint_as_float(rr[1]));
.LBB0_817:
	s_or_b64 exec, exec, s[8:9]
	global_load_dwordx4 v[146:149], v160, s[56:57] offset:256
	ds_read_b128 v[242:245], v201
	ds_read_b128 v[246:249], v201 offset:32
	v_add_f32_e32 v50, v66, v50
	v_add_u32_e32 v150, 0x6000, v150
	v_add_u32_e32 v152, 0x6000, v152
	v_add_u32_e32 v160, 0x100, v160
	v_add_f32_e32 v51, v67, v51
	v_add_f32_e32 v52, v68, v52
	v_add_f32_e32 v50, v51, v50
	v_add_f32_e32 v53, v69, v53
	v_add_f32_e32 v50, v52, v50
	v_add_f32_e32 v54, v70, v54
	v_add_f32_e32 v50, v53, v50
	v_add_f32_e32 v55, v71, v55
	v_add_f32_e32 v50, v54, v50
	v_max_f32_e32 v51, v82, v83
	v_add_f32_e32 v56, v72, v56
	v_add_f32_e32 v50, v55, v50
	v_max3_f32 v52, v84, v85, v99
	v_max3_f32 v51, v51, v98, v100
	v_add_f32_e32 v57, v73, v57
	v_add_f32_e32 v50, v56, v50
	v_max3_f32 v51, v51, v101, v86
	v_max3_f32 v52, v52, v88, v89
	v_add_f32_e32 v58, v74, v58
	v_add_f32_e32 v50, v57, v50
	v_max3_f32 v51, v51, v87, v102
	v_max3_f32 v52, v52, v104, v105
	v_add_f32_e32 v59, v75, v59
	v_add_f32_e32 v50, v58, v50
	v_max3_f32 v51, v51, v103, v90
	v_max3_f32 v52, v52, v92, v93
	v_add_f32_e32 v60, v76, v60
	v_add_f32_e32 v50, v59, v50
	v_max3_f32 v51, v51, v91, v106
	v_max3_f32 v52, v52, v108, v109
	v_add_f32_e32 v61, v77, v61
	v_add_f32_e32 v50, v60, v50
	v_max3_f32 v51, v51, v107, v94
	v_max3_f32 v52, v52, v96, v97
	v_add_f32_e32 v62, v78, v62
	v_add_f32_e32 v50, v61, v50
	v_max3_f32 v51, v51, v95, v110
	v_max3_f32 v52, v52, v112, v113
	v_add_f32_e32 v63, v79, v63
	v_add_f32_e32 v50, v62, v50
	v_max3_f32 v51, v51, v111, v52
	v_add_f32_e32 v64, v80, v64
	v_add_f32_e32 v50, v63, v50
	v_mov_b32_e32 v52, v51
	v_add_f32_e32 v65, v81, v65
	v_add_f32_e32 v50, v64, v50
	v_permlane32_swap_b32_e32 v51, v52
	v_add_f32_e32 v50, v65, v50
	v_add_f32_e32 v180, v203, v50
	v_max_f32_e32 v51, v51, v52
	v_cmp_lt_f32_e32 vcc, s97, v51
	s_cbranch_vccnz .Lat1_resc_b
	v_mov_b32_e32 v205, v204
.LBB0_820:
	v_exp_f32_e32 v163, v86
	v_exp_f32_e32 v162, v87
	s_waitcnt lgkmcnt(0)
	v_mfma_f32_32x32x16_bf16 v[50:65], v[242:245], v[114:117], v[34:49]
	v_exp_f32_e32 v82, v82
	v_exp_f32_e32 v83, v83
	v_exp_f32_e32 v84, v84
	v_exp_f32_e32 v85, v85
	v_exp_f32_e32 v87, v104
	v_exp_f32_e32 v86, v105
	v_mfma_f32_32x32x16_bf16 v[50:65], v[246:249], v[118:121], v[50:65]
	ds_read_b128 v[66:69], v201 offset:64
	ds_read_b128 v[70:73], v201 offset:96
	v_exp_f32_e32 v175, v102
	v_exp_f32_e32 v174, v103
	v_cvt_pk_bf16_f32 v102, v82, v83
	v_cvt_pk_bf16_f32 v103, v84, v85
	v_cvt_pk_bf16_f32 v104, v163, v162
	v_exp_f32_e32 v177, v96
	s_waitcnt lgkmcnt(1)
	v_mfma_f32_32x32x16_bf16 v[50:65], v[66:69], v[122:125], v[50:65]
	ds_read_b128 v[66:69], v201 offset:128
	v_exp_f32_e32 v176, v97
	v_exp_f32_e32 v98, v98
	v_exp_f32_e32 v99, v99
	v_exp_f32_e32 v100, v100
	v_exp_f32_e32 v101, v101
	v_add_f32_e32 v181, v98, v82
	s_waitcnt lgkmcnt(1)
	v_mfma_f32_32x32x16_bf16 v[50:65], v[70:73], v[126:129], v[50:65]
	ds_read_b128 v[166:169], v201 offset:6656
	ds_read_b128 v[170:173], v201 offset:6688
	ds_read_b128 v[182:185], v201 offset:6720
	ds_read_b128 v[186:189], v201 offset:6752
	ds_read_b128 v[70:73], v201 offset:160
	ds_read_b128 v[210:213], v201 offset:6784
	ds_read_b128 v[214:217], v201 offset:6816
	v_add_f32_e32 v203, v99, v83
	v_add_f32_e32 v181, 0, v181
	v_add_f32_e32 v228, v100, v84
	v_add_f32_e32 v181, v203, v181
	v_add_f32_e32 v229, v101, v85
	s_waitcnt lgkmcnt(7)
	v_mfma_f32_32x32x16_bf16 v[50:65], v[66:69], v[130:133], v[50:65]
	v_add_f32_e64 v218, v174, v162
	v_add_f32_e64 v219, v175, v163
	s_add_i32 s12, s12, 2
	s_add_i32 s0, s90, 2
	s_add_i32 s1, s89, 2
	s_waitcnt lgkmcnt(2)
	v_mfma_f32_32x32x16_bf16 v[50:65], v[70:73], v[134:137], v[50:65]
	s_cmp_ge_u32 s12, s29
	v_mfma_f32_32x32x16_bf16 v[66:81], v[166:169], v[114:117], v[34:49]
	v_exp_f32_e32 v167, v88
	v_exp_f32_e32 v166, v89
	v_exp_f32_e32 v169, v90
	v_exp_f32_e32 v89, v106
	v_exp_f32_e32 v168, v91
	v_exp_f32_e32 v88, v107
	v_exp_f32_e32 v91, v108
	v_mfma_f32_32x32x16_bf16 v[66:81], v[170:173], v[118:121], v[66:81]
	v_exp_f32_e32 v90, v109
	ds_read2_b64 v[106:109], v209 offset0:64 offset1:66
	v_exp_f32_e32 v171, v92
	v_exp_f32_e32 v170, v93
	v_exp_f32_e32 v93, v110
	v_exp_f32_e32 v92, v111
	v_mfma_f32_32x32x16_bf16 v[66:81], v[182:185], v[122:125], v[66:81]
	v_cvt_pk_bf16_f32 v105, v167, v166
	v_exp_f32_e32 v173, v94
	v_exp_f32_e32 v172, v95
	v_exp_f32_e32 v95, v112
	v_exp_f32_e32 v94, v113
	ds_read2_b64 v[110:113], v209 offset0:68 offset1:70
	v_add_f32_e32 v220, v86, v166
	v_add_f32_e32 v221, v87, v167
	v_mfma_f32_32x32x16_bf16 v[66:81], v[186:189], v[126:129], v[66:81]
	v_add_f32_e32 v222, v88, v168
	v_add_f32_e32 v223, v89, v169
	v_add_f32_e32 v96, v90, v170
	v_add_f32_e32 v97, v91, v171
	v_add_f32_e32 v224, v92, v172
	v_add_f32_e32 v225, v93, v173
	v_add_f32_e32 v226, v94, v176
	v_add_f32_e32 v227, v95, v177
	s_waitcnt lgkmcnt(3)
	v_mfma_f32_32x32x16_bf16 v[66:81], v[210:213], v[130:133], v[66:81]
	v_add_u32_e32 v210, 0x9800, v179
	ds_read2_b64 v[182:185], v210 offset0:96 offset1:98
	s_nop 0
	v_cvt_pk_bf16_f32 v212, v89, v88
	s_waitcnt lgkmcnt(2)
	v_mfma_f32_32x32x16_bf16 v[2:17], v[106:109], v[102:105], v[2:17]
	v_cvt_pk_bf16_f32 v106, v169, v168
	v_cvt_pk_bf16_f32 v107, v171, v170
	v_cvt_pk_bf16_f32 v108, v173, v172
	v_cvt_pk_bf16_f32 v109, v177, v176
	s_waitcnt lgkmcnt(0)
	v_mfma_f32_32x32x16_bf16 v[18:33], v[182:185], v[102:105], v[18:33]
	ds_read2_b64 v[102:105], v210 offset0:100 offset1:102
	v_cvt_pk_bf16_f32 v184, v175, v174
	v_cvt_pk_bf16_f32 v185, v87, v86
	v_cvt_pk_bf16_f32 v182, v98, v99
	v_cvt_pk_bf16_f32 v183, v100, v101
	v_mfma_f32_32x32x16_bf16 v[2:17], v[110:113], v[106:109], v[2:17]
	ds_read2_b64 v[110:113], v209 offset0:72 offset1:74
	ds_read2_b64 v[186:189], v210 offset0:104 offset1:106
	s_waitcnt lgkmcnt(2)
	v_mfma_f32_32x32x16_bf16 v[18:33], v[102:105], v[106:109], v[18:33]
	s_waitcnt lgkmcnt(0)
	v_mfma_f32_32x32x16_bf16 v[2:17], v[110:113], v[182:185], v[2:17]
	v_add_f32_e32 v110, v228, v181
	v_add_f32_e32 v110, v229, v110
	v_add_f32_e32 v110, v219, v110
	v_add_f32_e32 v110, v218, v110
	v_add_f32_e32 v110, v221, v110
	v_add_f32_e32 v110, v220, v110
	v_add_f32_e32 v110, v223, v110
	v_mfma_f32_32x32x16_bf16 v[18:33], v[186:189], v[182:185], v[18:33]
	v_add_f32_e32 v110, v222, v110
	v_add_f32_e32 v97, v97, v110
	v_add_f32_e32 v96, v96, v97
	v_add_f32_e32 v96, v225, v96
	v_add_f32_e32 v96, v224, v96
	v_add_f32_e32 v96, v227, v96
	v_add_f32_e32 v96, v226, v96
	v_mfma_f32_32x32x16_bf16 v[66:81], v[214:217], v[134:137], v[66:81]
	v_add_f32_e32 v203, v180, v96
	v_cvt_pk_bf16_f32 v213, v91, v90
	v_cvt_pk_bf16_f32 v214, v93, v92
	v_cvt_pk_bf16_f32 v215, v95, v94
	ds_read2_b64 v[102:105], v209 offset0:76 offset1:78
	ds_read2_b64 v[106:109], v210 offset0:108 offset1:110
	s_waitcnt lgkmcnt(0)
	v_mfma_f32_32x32x16_bf16 v[2:17], v[102:105], v[212:215], v[2:17]
	v_mfma_f32_32x32x16_bf16 v[18:33], v[106:109], v[212:215], v[18:33]
	s_cbranch_scc0 .LBB0_800
	s_add_i32 s91, s29, 4
	s_mov_b64 s[8:9], -1
	s_cmp_lt_u32 s12, s91
	v_lshlrev_b32_e32 v158, 2, v178
	s_cbranch_scc1 .LBB0_823
	v_lshlrev_b32_e32 v0, 2, v178
	s_mov_b64 s[8:9], 0

; DI float rowmax32(const f32x16& p0, const f32x16& p1) {
;     float a = fmaxf(fmaxf(p0[0], p0[1]), p1[0]), b = fmaxf(fmaxf(p0[2], p0[3]), p1[1]); a = fmaxf(fmaxf(a, p1[2]), p1[3]);
; #pragma unroll
;     for (int r = 4; r < 16; r += 4) { a = fmaxf(fmaxf(a, p0[r]), p0[r + 1]); b = fmaxf(fmaxf(b, p0[r + 2]), p0[r + 3]); a = fmaxf(fmaxf(a, p1[r]), p1[r + 1]); b = fmaxf(fmaxf(b, p1[r + 2]), p1[r + 3]); }
;     const float m = fmaxf(a, b);
;     const auto rr = __builtin_amdgcn_permlane32_swap(__float_as_uint(m), __float_as_uint(m), false, false);
;     return fmaxf(__uint_as_float(rr[0]), __uint_as_float(rr[1]));
.LBB0_873:
	s_or_b64 exec, exec, s[8:9]
	global_load_dwordx4 v[160:163], v182, s[56:57] offset:256
	ds_read_b128 v[248:251], v203
	ds_read_b128 v[252:255], v203 offset:32
	v_add_f32_e32 v4, v82, v66
	v_add_u32_e32 v178, 0x6000, v178
	v_add_u32_e32 v180, 0x6000, v180
	v_add_u32_e32 v182, 0x100, v182
	v_add_f32_e32 v2, v80, v64
	v_add_f32_e32 v3, v81, v65
	v_add_f32_e32 v2, v3, v2
	v_add_f32_e32 v5, v83, v67
	v_add_f32_e32 v2, v4, v2
	v_add_f32_e32 v6, v84, v68
	v_add_f32_e32 v2, v5, v2
	v_add_f32_e32 v7, v85, v69
	v_add_f32_e32 v2, v6, v2
	v_max_f32_e32 v3, v96, v97
	v_add_f32_e32 v8, v86, v70
	v_add_f32_e32 v2, v7, v2
	v_max3_f32 v4, v98, v99, v113
	v_max3_f32 v3, v3, v112, v114
	v_add_f32_e32 v9, v87, v71
	v_add_f32_e32 v2, v8, v2
	v_max3_f32 v3, v3, v115, v100
	v_max3_f32 v4, v4, v102, v103
	v_add_f32_e32 v10, v88, v72
	v_add_f32_e32 v2, v9, v2
	v_max3_f32 v3, v3, v101, v116
	v_max3_f32 v4, v4, v118, v119
	v_add_f32_e32 v11, v89, v73
	v_add_f32_e32 v2, v10, v2
	v_max3_f32 v3, v3, v117, v104
	v_max3_f32 v4, v4, v106, v107
	v_add_f32_e32 v12, v90, v74
	v_add_f32_e32 v2, v11, v2
	v_max3_f32 v3, v3, v105, v120
	v_max3_f32 v4, v4, v122, v123
	v_add_f32_e32 v13, v91, v75
	v_add_f32_e32 v2, v12, v2
	v_max3_f32 v3, v3, v121, v108
	v_max3_f32 v4, v4, v110, v111
	v_add_f32_e32 v14, v92, v76
	v_add_f32_e32 v2, v13, v2
	v_max3_f32 v3, v3, v109, v124
	v_max3_f32 v4, v4, v126, v127
	v_add_f32_e32 v15, v93, v77
	v_add_f32_e32 v2, v14, v2
	v_max3_f32 v3, v3, v125, v4
	v_add_f32_e32 v64, v94, v78
	v_add_f32_e32 v2, v15, v2
	v_mov_b32_e32 v4, v3
	v_add_f32_e32 v65, v95, v79
	v_add_f32_e32 v2, v64, v2
	v_permlane32_swap_b32_e32 v3, v4
	v_add_f32_e32 v2, v65, v2
	v_add_f32_e32 v188, v208, v2
	v_max_f32_e32 v3, v3, v4
	v_cmp_lt_f32_e32 vcc, s97, v3
	s_cbranch_vccnz .Lat2_resc_b
	v_mov_b32_e32 v210, v209
.LBB0_875:
	v_exp_f32_e32 v11, v100
	v_exp_f32_e32 v10, v101
	v_exp_f32_e32 v96, v96
	s_waitcnt lgkmcnt(0)
	v_mfma_f32_32x32x16_bf16 v[64:79], v[248:251], v[128:131], v[48:63]
	v_exp_f32_e32 v97, v97
	v_exp_f32_e32 v98, v98
	v_exp_f32_e32 v99, v99
	v_exp_f32_e32 v185, v126
	v_exp_f32_e32 v184, v127
	v_cvt_pk_bf16_f32 v100, v96, v97
	v_cvt_pk_bf16_f32 v101, v98, v99
	v_mfma_f32_32x32x16_bf16 v[64:79], v[252:255], v[132:135], v[64:79]
	ds_read_b128 v[2:5], v203 offset:64
	ds_read_b128 v[6:9], v203 offset:96
	v_exp_f32_e32 v112, v112
	v_exp_f32_e32 v113, v113
	v_exp_f32_e32 v114, v114
	v_exp_f32_e32 v115, v115
	v_add_f32_e32 v189, v112, v96
	v_add_f32_e32 v208, v113, v97
	s_waitcnt lgkmcnt(1)
	v_mfma_f32_32x32x16_bf16 v[64:79], v[2:5], v[136:139], v[64:79]
	ds_read_b128 v[2:5], v203 offset:128
	v_add_f32_e32 v211, v114, v98
	v_add_f32_e32 v236, v115, v99
	s_add_i32 s76, s76, 2
	s_waitcnt lgkmcnt(1)
	v_mfma_f32_32x32x16_bf16 v[64:79], v[6:9], v[140:143], v[64:79]
	ds_read_b128 v[6:9], v203 offset:160
	s_cmp_ge_u32 s76, s15
	s_waitcnt lgkmcnt(1)
	v_mfma_f32_32x32x16_bf16 v[64:79], v[2:5], v[144:147], v[64:79]
	ds_read_b128 v[2:5], v203 offset:6656
	ds_read_b128 v[12:15], v203 offset:6688
	ds_read_b128 v[212:215], v203 offset:6720
	ds_read_b128 v[216:219], v203 offset:6752
	ds_read_b128 v[220:223], v203 offset:6784
	ds_read_b128 v[224:227], v203 offset:6816
	s_waitcnt lgkmcnt(4)
	v_mfma_f32_32x32x16_bf16 v[80:95], v[2:5], v[128:131], v[48:63]
	v_exp_f32_e32 v3, v116
	v_exp_f32_e32 v2, v117
	v_exp_f32_e32 v5, v118
	v_exp_f32_e32 v4, v119
	v_exp_f32_e32 v117, v104
	v_exp_f32_e32 v116, v105
	v_exp_f32_e32 v119, v106
	v_mfma_f32_32x32x16_bf16 v[80:95], v[12:15], v[132:135], v[80:95]
	v_exp_f32_e32 v15, v102
	v_exp_f32_e32 v14, v103
	v_exp_f32_e32 v118, v107
	v_cvt_pk_bf16_f32 v102, v11, v10
	v_exp_f32_e32 v13, v124
	v_exp_f32_e32 v12, v125
	s_waitcnt lgkmcnt(2)
	v_mfma_f32_32x32x16_bf16 v[80:95], v[212:215], v[136:139], v[80:95]
	v_cvt_pk_bf16_f32 v124, v117, v116
	v_cvt_pk_bf16_f32 v125, v119, v118
	v_add_f32_e32 v190, v2, v10
	v_add_f32_e32 v191, v3, v11
	v_add_f32_e32 v228, v4, v14
	v_add_f32_e32 v229, v5, v15
	v_mfma_f32_32x32x16_bf16 v[80:95], v[216:219], v[140:143], v[80:95]
	v_mfma_f32_32x32x16_bf16 v[64:79], v[6:9], v[148:151], v[64:79]
	v_exp_f32_e32 v7, v120
	v_exp_f32_e32 v6, v121
	v_exp_f32_e32 v121, v108
	v_exp_f32_e32 v120, v109
	v_exp_f32_e32 v9, v122
	v_exp_f32_e32 v8, v123
	s_waitcnt lgkmcnt(1)
	v_mfma_f32_32x32x16_bf16 v[80:95], v[220:223], v[144:147], v[80:95]
	v_exp_f32_e32 v123, v110
	v_exp_f32_e32 v122, v111
	ds_read2_b64 v[104:107], v246 offset0:64 offset1:66
	v_cvt_pk_bf16_f32 v103, v15, v14
	ds_read2_b64 v[108:111], v247 offset0:96 offset1:98
	s_waitcnt lgkmcnt(1)
	v_mfma_f32_32x32x16_bf16 v[32:47], v[104:107], v[100:103], v[32:47]
	ds_read2_b64 v[104:107], v246 offset0:68 offset1:70
	v_cvt_pk_bf16_f32 v126, v121, v120
	v_add_f32_e32 v230, v6, v116
	v_add_f32_e32 v231, v7, v117
	v_cvt_pk_bf16_f32 v216, v7, v6
	v_add_f32_e32 v232, v8, v118
	v_add_f32_e32 v233, v9, v119
	v_add_f32_e32 v234, v12, v120
	v_add_f32_e32 v235, v13, v121
	s_waitcnt lgkmcnt(1)
	v_mfma_f32_32x32x16_bf16 v[16:31], v[108:111], v[100:103], v[16:31]
	v_cvt_pk_bf16_f32 v127, v123, v122
	ds_read2_b64 v[100:103], v247 offset0:100 offset1:102
	v_cvt_pk_bf16_f32 v110, v3, v2
	v_cvt_pk_bf16_f32 v108, v112, v113
	v_cvt_pk_bf16_f32 v109, v114, v115
	s_waitcnt lgkmcnt(1)
	v_mfma_f32_32x32x16_bf16 v[32:47], v[104:107], v[124:127], v[32:47]
	v_add_f32_e32 v220, v184, v122
	v_add_f32_e32 v221, v185, v123
	v_cvt_pk_bf16_f32 v111, v5, v4
	ds_read2_b64 v[104:107], v246 offset0:72 offset1:74
	ds_read2_b64 v[212:215], v247 offset0:104 offset1:106
	s_waitcnt lgkmcnt(2)
	v_mfma_f32_32x32x16_bf16 v[16:31], v[100:103], v[124:127], v[16:31]
	s_nop 0
	v_cvt_pk_bf16_f32 v217, v9, v8
	s_nop 0
	v_cvt_pk_bf16_f32 v218, v13, v12
	s_waitcnt lgkmcnt(1)
	v_mfma_f32_32x32x16_bf16 v[32:47], v[104:107], v[108:111], v[32:47]
	v_cvt_pk_bf16_f32 v219, v185, v184
	ds_read2_b64 v[100:103], v246 offset0:76 offset1:78
	ds_read2_b64 v[104:107], v247 offset0:108 offset1:110
	v_add_f32_e32 v0, 0, v189
	v_add_f32_e32 v0, v208, v0
	v_add_f32_e32 v0, v211, v0
	v_add_f32_e32 v0, v236, v0
	s_waitcnt lgkmcnt(2)
	v_mfma_f32_32x32x16_bf16 v[16:31], v[212:215], v[108:111], v[16:31]
	v_add_f32_e32 v0, v191, v0
	v_add_f32_e32 v0, v190, v0
	v_add_f32_e32 v0, v229, v0
	v_add_f32_e32 v0, v228, v0
	v_add_f32_e32 v0, v231, v0
	v_add_f32_e32 v0, v230, v0
	v_add_f32_e32 v0, v233, v0
	v_mfma_f32_32x32x16_bf16 v[80:95], v[224:227], v[148:151], v[80:95]
	v_add_f32_e32 v0, v232, v0
	v_add_f32_e32 v0, v235, v0
	v_add_f32_e32 v0, v234, v0
	v_add_f32_e32 v0, v221, v0
	v_add_f32_e32 v0, v220, v0
	v_add_f32_e32 v208, v188, v0
	s_waitcnt lgkmcnt(0)
	v_mfma_f32_32x32x16_bf16 v[32:47], v[100:103], v[216:219], v[32:47]
	v_mfma_f32_32x32x16_bf16 v[16:31], v[104:107], v[216:219], v[16:31]
	s_cbranch_scc1 .LBB0_894

.LBB0_880:
	s_or_b64 exec, exec, s[8:9]
	global_load_dwordx4 v[6:9], v182, s[56:57] offset:128
	ds_read_b128 v[112:115], v203 offset:13312
	ds_read_b128 v[116:119], v203 offset:13344
	v_max_f32_e32 v96, v64, v65
	v_max3_f32 v97, v66, v67, v81
	v_max3_f32 v96, v96, v80, v82
	v_max3_f32 v96, v96, v83, v68
	v_max3_f32 v97, v97, v70, v71
	v_max3_f32 v96, v96, v69, v84
	v_max3_f32 v97, v97, v86, v87
	v_max3_f32 v96, v96, v85, v72
	v_max3_f32 v97, v97, v74, v75
	v_max3_f32 v96, v96, v73, v88
	v_max3_f32 v97, v97, v90, v91
	v_max3_f32 v96, v96, v89, v76
	v_max3_f32 v97, v97, v78, v79
	v_max3_f32 v96, v96, v77, v92
	v_max3_f32 v97, v97, v94, v95
	v_max3_f32 v96, v96, v93, v97
	v_mov_b32_e32 v97, v96
	s_cmp_eq_u32 s76, 0
	s_nop 0
	v_permlane32_swap_b32_e32 v96, v97
	v_max_f32_e32 v96, v96, v97
	s_cbranch_scc1 .Lat2_first
	v_cmp_lt_f32_e32 vcc, s97, v96
	s_cbranch_vccnz .Lat2_resc
	v_mov_b32_e32 v209, v210
.LBB0_889:
	v_exp_f32_e32 v64, v64
	s_waitcnt lgkmcnt(0)
	v_mfma_f32_32x32x16_bf16 v[96:111], v[112:115], v[128:131], v[48:63]
	v_exp_f32_e32 v65, v65
	v_exp_f32_e32 v66, v66
	v_exp_f32_e32 v67, v67
	v_exp_f32_e32 v68, v68
	v_exp_f32_e32 v69, v69
	v_exp_f32_e32 v70, v70
	v_exp_f32_e32 v71, v71
	v_mfma_f32_32x32x16_bf16 v[96:111], v[116:119], v[132:135], v[96:111]
	ds_read_b128 v[112:115], v203 offset:13376
	ds_read_b128 v[116:119], v203 offset:13408
	v_exp_f32_e32 v72, v72
	v_exp_f32_e32 v73, v73
	v_exp_f32_e32 v74, v74
	v_exp_f32_e32 v75, v75
	v_exp_f32_e32 v76, v76
	s_waitcnt lgkmcnt(0)
	v_mfma_f32_32x32x16_bf16 v[96:111], v[112:115], v[136:139], v[96:111]
	v_exp_f32_e32 v77, v77
	v_exp_f32_e32 v78, v78
	v_exp_f32_e32 v79, v79
	v_exp_f32_e32 v80, v80
	v_exp_f32_e32 v81, v81
	v_exp_f32_e32 v82, v82
	v_exp_f32_e32 v83, v83
	v_mfma_f32_32x32x16_bf16 v[96:111], v[116:119], v[140:143], v[96:111]
	ds_read_b128 v[112:115], v203 offset:13440
	ds_read_b128 v[116:119], v203 offset:13472
	ds_read_b128 v[156:159], v203 offset:19968
	ds_read_b128 v[160:163], v203 offset:20000
	v_exp_f32_e32 v84, v84
	v_exp_f32_e32 v85, v85
	v_exp_f32_e32 v86, v86
	v_exp_f32_e32 v87, v87
	v_exp_f32_e32 v88, v88
	s_waitcnt lgkmcnt(2)
	v_mfma_f32_32x32x16_bf16 v[96:111], v[112:115], v[144:147], v[96:111]
	v_exp_f32_e32 v89, v89
	v_exp_f32_e32 v90, v90
	v_exp_f32_e32 v91, v91
	v_exp_f32_e32 v92, v92
	v_exp_f32_e32 v93, v93
	v_exp_f32_e32 v94, v94
	v_exp_f32_e32 v95, v95
	v_mfma_f32_32x32x16_bf16 v[96:111], v[116:119], v[148:151], v[96:111]
	s_waitcnt lgkmcnt(0)
	v_mfma_f32_32x32x16_bf16 v[112:127], v[156:159], v[128:131], v[48:63]
	v_mfma_f32_32x32x16_bf16 v[112:127], v[160:163], v[132:135], v[112:127]
	ds_read_b128 v[156:159], v203 offset:20032
	ds_read_b128 v[160:163], v203 offset:20064
	s_waitcnt lgkmcnt(0)
	v_mfma_f32_32x32x16_bf16 v[112:127], v[156:159], v[136:139], v[112:127]
	v_mfma_f32_32x32x16_bf16 v[112:127], v[160:163], v[140:143], v[112:127]
	ds_read_b128 v[156:159], v203 offset:20096
	ds_read_b128 v[160:163], v203 offset:20128
	ds_read2_b64 v[188:191], v244 offset0:4 offset1:6
	s_waitcnt lgkmcnt(2)
	v_mfma_f32_32x32x16_bf16 v[112:127], v[156:159], v[144:147], v[112:127]
	ds_read2_b64 v[156:159], v244 offset1:2
	s_waitcnt lgkmcnt(2)
	v_mfma_f32_32x32x16_bf16 v[112:127], v[160:163], v[148:151], v[112:127]
	v_cvt_pk_bf16_f32 v160, v64, v65
	v_cvt_pk_bf16_f32 v161, v66, v67
	v_cvt_pk_bf16_f32 v162, v68, v69
	v_cvt_pk_bf16_f32 v163, v70, v71
	s_waitcnt lgkmcnt(0)
	s_nop 0
	v_mfma_f32_32x32x16_bf16 v[32:47], v[156:159], v[160:163], v[32:47]
	ds_read2_b64 v[156:159], v245 offset0:32 offset1:34
	s_waitcnt lgkmcnt(0)
	v_mfma_f32_32x32x16_bf16 v[16:31], v[156:159], v[160:163], v[16:31]
	ds_read2_b64 v[160:163], v245 offset0:36 offset1:38
	v_cvt_pk_bf16_f32 v156, v72, v73
	v_cvt_pk_bf16_f32 v157, v74, v75
	v_cvt_pk_bf16_f32 v158, v76, v77
	v_cvt_pk_bf16_f32 v159, v78, v79
	s_nop 1
	v_mfma_f32_32x32x16_bf16 v[32:47], v[188:191], v[156:159], v[32:47]
	ds_read2_b64 v[188:191], v244 offset0:8 offset1:10
	s_waitcnt lgkmcnt(1)
	v_mfma_f32_32x32x16_bf16 v[16:31], v[160:163], v[156:159], v[16:31]
	ds_read2_b64 v[160:163], v245 offset0:40 offset1:42
	v_cvt_pk_bf16_f32 v156, v80, v81
	v_cvt_pk_bf16_f32 v157, v82, v83
	v_cvt_pk_bf16_f32 v158, v84, v85
	v_cvt_pk_bf16_f32 v159, v86, v87
	s_waitcnt lgkmcnt(1)
	s_nop 0
	v_mfma_f32_32x32x16_bf16 v[32:47], v[188:191], v[156:159], v[32:47]
	ds_read2_b64 v[188:191], v244 offset0:12 offset1:14
	s_waitcnt lgkmcnt(1)
	v_mfma_f32_32x32x16_bf16 v[16:31], v[160:163], v[156:159], v[16:31]
	ds_read2_b64 v[160:163], v245 offset0:44 offset1:46
	v_cvt_pk_bf16_f32 v156, v88, v89
	v_cvt_pk_bf16_f32 v157, v90, v91
	v_cvt_pk_bf16_f32 v158, v92, v93
	v_cvt_pk_bf16_f32 v159, v94, v95
	s_waitcnt vmcnt(1)
	ds_write_b128 v201, v[2:5]
	s_waitcnt lgkmcnt(2)
	v_mfma_f32_32x32x16_bf16 v[32:47], v[188:191], v[156:159], v[32:47]
	s_waitcnt lgkmcnt(1)
	v_mfma_f32_32x32x16_bf16 v[16:31], v[160:163], v[156:159], v[16:31]
	s_and_saveexec_b64 s[8:9], s[6:7]
	ds_write_b128 v169, v[152:155]
	s_or_b64 exec, exec, s[8:9]
	s_waitcnt vmcnt(0)
	ds_write2_b64 v243, v[6:7], v[8:9] offset1:1
	s_waitcnt lgkmcnt(0)
	s_barrier
	global_load_dwordx4 v[156:159], v180, s[54:55]
	s_and_saveexec_b64 s[8:9], s[6:7]
	s_cbranch_execz .LBB0_873
	global_load_dwordx4 v[152:155], v178, s[54:55]
	s_branch .LBB0_873
